# grid barriers: L1 invalidate (buffer_inv sc1) issued before the poll loop instead of after it, so it overlaps the wait
# speedup vs baseline: 1.0791x; 1.0169x over previous
.Lxb_poll_0:
	v_readlane_b32 s8, v255, 12
	v_readlane_b32 s9, v255, 13
	s_nop 4
	buffer_inv sc1

.Lxb_done_0:
.LBB0_353:
	s_or_b64 exec, exec, s[0:1]
	v_readlane_b32 s8, v254, 12
	v_readlane_b32 s12, v254, 16
	v_readlane_b32 s13, v254, 17
	v_readlane_b32 s14, v254, 18
	v_readlane_b32 s15, v254, 19
	v_readlane_b32 s16, v254, 20
	v_readlane_b32 s17, v254, 21
	v_readlane_b32 s18, v254, 22
	v_readlane_b32 s19, v254, 23
	s_mul_i32 s90, s52, 0x50c000
	v_readlane_b32 s20, v254, 24
	v_readlane_b32 s21, v254, 25
	v_readlane_b32 s22, v254, 26
	v_readlane_b32 s23, v254, 27
	s_mov_b64 s[12:13], s[16:17]
	s_lshl_b64 s[0:1], s[90:91], 1
	v_readlane_b32 s10, v254, 14
	s_mov_b64 s[14:15], s[18:19]
	s_add_u32 s10, s14, s0
	s_addc_u32 s40, s15, s1
	s_mov_b32 s41, 0
	v_writelane_b32 v255, s52, 52
	s_waitcnt lgkmcnt(0)
	s_barrier
	v_readlane_b32 s9, v254, 13
	v_readlane_b32 s11, v254, 15
	s_mov_b64 s[16:17], s[20:21]
	s_mov_b64 s[18:19], s[22:23]
	s_branch .LBB0_356

.Lxb_done_1:
.LBB0_513:
	s_or_b64 exec, exec, s[0:1]
	v_readfirstlane_b32 s0, v234
	s_lshr_b32 s1, s0, 8
	v_readlane_b32 s2, v255, 19
	s_add_i32 s12, s1, s2
	s_cmp_gt_u32 s12, 23
	s_waitcnt lgkmcnt(0)
	s_barrier
	s_cbranch_scc1 .LBB0_521
	s_lshl_b32 s0, s0, 8
	s_and_b32 s0, s0, 0x7fff0000
	s_add_i32 s13, s0, 0

.Lxb_done_2:
.LBB0_597:
	s_or_b64 exec, exec, s[0:1]
	v_readfirstlane_b32 s0, v234
	s_lshr_b32 s0, s0, 8
	s_add_i32 s0, s0, s92
	s_waitcnt lgkmcnt(0)
	v_mov_b32_e32 v0, v235
	s_cmpk_gt_i32 s0, 0x7f
	s_movk_i32 s43, 0x140
	s_barrier
	s_cbranch_scc1 .LBB0_599
	v_readfirstlane_b32 s0, v234
	s_lshr_b32 s0, s0, 8
	s_add_i32 s43, s0, s92

.Lxb_done_3:
.LBB0_698:
	s_or_b64 exec, exec, s[0:1]
	v_readfirstlane_b32 s0, v234
	s_lshr_b32 s1, s0, 8
	v_readlane_b32 s2, v255, 19
	s_add_i32 s12, s1, s2
	s_cmp_gt_u32 s12, 47
	s_waitcnt lgkmcnt(0)
	s_barrier
	s_cbranch_scc1 .LBB0_706
	s_lshl_b32 s0, s0, 8
	s_and_b32 s0, s0, 0x7fff0000
	s_lshl_b32 s90, s52, 9
	v_readlane_b32 s16, v253, 60
	s_add_i32 s13, s0, 0
	s_lshl_b64 s[0:1], s[90:91], 2
	v_readlane_b32 s26, v254, 6
	v_readlane_b32 s27, v254, 7
	s_add_u32 s36, s26, s0
	s_addc_u32 s37, s27, s1
	s_mov_b32 s8, 0xc000
	s_mov_b32 s9, 0x24000
	v_readlane_b32 s17, v253, 61
	v_readlane_b32 s18, v253, 62
	v_readlane_b32 s19, v253, 63
	v_readlane_b32 s20, v254, 0
	v_readlane_b32 s21, v254, 1
	v_readlane_b32 s22, v254, 2
	v_readlane_b32 s23, v254, 3
	v_readlane_b32 s24, v254, 4
	v_readlane_b32 s25, v254, 5
	v_readlane_b32 s28, v254, 8
	v_readlane_b32 s29, v254, 9
	v_readlane_b32 s30, v254, 10
	v_readlane_b32 s31, v254, 11

.Lxb_done_4:
.LBB0_761:
	s_or_b64 exec, exec, s[0:1]
	v_readfirstlane_b32 s0, v234
	v_readlane_b32 s8, v254, 12
	s_lshl_b32 s0, s0, 8
	v_readlane_b32 s12, v254, 16
	v_readlane_b32 s13, v254, 17
	v_readlane_b32 s14, v254, 18
	v_readlane_b32 s15, v254, 19
	v_readlane_b32 s16, v254, 20
	v_readlane_b32 s17, v254, 21
	v_readlane_b32 s18, v254, 22
	v_readlane_b32 s19, v254, 23
	s_and_b32 s0, s0, 0x7fff0000
	v_readlane_b32 s20, v254, 24
	v_readlane_b32 s21, v254, 25
	v_readlane_b32 s22, v254, 26
	v_readlane_b32 s23, v254, 27
	s_mov_b64 s[12:13], s[16:17]
	s_add_i32 s36, s0, 0
	s_lshl_b32 s0, s52, 19
	s_mov_b64 s[14:15], s[18:19]
	s_mov_b64 s[16:17], s[20:21]
	v_readlane_b32 s9, v254, 13
	v_readlane_b32 s10, v254, 14
	v_readlane_b32 s11, v254, 15
	s_mov_b64 s[18:19], s[22:23]
	s_add_u32 s37, s16, s0
	s_addc_u32 s38, s17, 0
	s_lshl_b32 s90, s52, 9
	v_readlane_b32 s8, v253, 60
	s_lshl_b64 s[2:3], s[90:91], 2
	v_readlane_b32 s12, v254, 0
	v_readlane_b32 s22, v254, 10
	v_readlane_b32 s13, v254, 1
	v_readlane_b32 s23, v254, 11
	s_add_u32 s12, s22, s2
	s_addc_u32 s13, s23, s3
	s_mov_b32 s39, 0
	s_waitcnt lgkmcnt(0)
	s_barrier
	v_readlane_b32 s9, v253, 61
	v_readlane_b32 s10, v253, 62
	v_readlane_b32 s11, v253, 63
	v_readlane_b32 s14, v254, 2
	v_readlane_b32 s15, v254, 3
	v_readlane_b32 s16, v254, 4
	v_readlane_b32 s17, v254, 5
	v_readlane_b32 s18, v254, 6
	v_readlane_b32 s19, v254, 7
	v_readlane_b32 s20, v254, 8
	v_readlane_b32 s21, v254, 9
	s_branch .LBB0_763

.Lxb_done_5:
.LBB0_824:
	s_or_b64 exec, exec, s[0:1]
	v_readlane_b32 s0, v255, 24
	v_readlane_b32 s1, v255, 25
	s_andn2_b64 vcc, exec, s[0:1]
	s_waitcnt lgkmcnt(0)
	s_barrier
	s_cbranch_vccnz .LBB0_840
	v_readlane_b32 s8, v254, 12
	v_readlane_b32 s12, v254, 16
	v_readlane_b32 s13, v254, 17
	v_readlane_b32 s14, v254, 18
	v_readlane_b32 s15, v254, 19
	v_readlane_b32 s16, v254, 20
	v_readlane_b32 s17, v254, 21
	v_readlane_b32 s18, v254, 22
	v_readlane_b32 s19, v254, 23
	v_readlane_b32 s20, v254, 24
	v_readlane_b32 s21, v254, 25
	v_readlane_b32 s22, v254, 26
	v_readlane_b32 s23, v254, 27
	s_mov_b64 s[12:13], s[16:17]
	s_lshl_b32 s0, s52, 20
	s_mov_b64 s[14:15], s[18:19]
	s_mov_b64 s[16:17], s[20:21]
	s_mov_b64 s[18:19], s[22:23]
	s_add_u32 s40, s18, s0
	s_addc_u32 s41, s19, 0
	v_readlane_b32 s44, v253, 0
	v_readlane_b32 s45, v253, 1
	s_add_u32 s43, s44, s0
	s_addc_u32 s44, s45, 0
	s_mov_b32 s45, 0
	v_readlane_b32 s0, v255, 33
	s_movk_i32 s8, 0x1000
	v_readlane_b32 s9, v254, 13
	v_readlane_b32 s10, v254, 14
	v_readlane_b32 s11, v254, 15
	v_readlane_b32 s46, v253, 2
	v_readlane_b32 s47, v253, 3
	v_readlane_b32 s48, v253, 4
	v_readlane_b32 s49, v253, 5
	v_readlane_b32 s50, v253, 6
	v_readlane_b32 s51, v253, 7
	s_branch .LBB0_827

.Lxb_done_6:
.LBB0_1010:
	s_or_b64 exec, exec, s[0:1]
	v_readlane_b32 s44, v253, 0
	s_lshl_b32 s0, s52, 21
	v_readlane_b32 s46, v253, 2
	v_readlane_b32 s47, v253, 3
	v_readlane_b32 s50, v253, 6
	s_add_u32 s90, s46, s0
	v_readlane_b32 s51, v253, 7
	s_addc_u32 s43, s47, 0
	s_mov_b32 s50, 0
	s_waitcnt lgkmcnt(0)
	s_barrier
	v_readlane_b32 s45, v253, 1
	v_readlane_b32 s48, v253, 4
	v_readlane_b32 s49, v253, 5
	s_branch .LBB0_1014

.Lxb_done_7:
	s_branch .LBB0_290
